# ten-chunk workgroups' conv prologue: the 31 tap loads no longer throttled to 8 in flight (pair copies deferred to the single counted wait before the unit loop)
# speedup vs baseline: 1.0072x; 1.0072x over previous
.LBB0_317:
	s_andn2_b64 vcc, exec, s[28:29]
	s_cbranch_vccnz .LBB0_345
	s_waitcnt vmcnt(0)
	v_mov_b32_e32 v1, v242
	s_load_dwordx8 s[44:51], s[0:1], 0x38
	v_mov_b32_e32 v2, 2
	v_lshlrev_b32_sdwa v130, v2, v1 dst_sel:DWORD dst_unused:UNUSED_PAD src0_sel:DWORD src1_sel:BYTE_0
	v_readlane_b32 s8, v254, 39
	v_readlane_b32 s9, v254, 40
	s_waitcnt lgkmcnt(0)
	v_lshl_add_u64 v[2:3], s[44:45], 0, v[130:131]
	v_lshl_add_u64 v[4:5], v[2:3], 0, s[62:63]
	global_load_dword v42, v[4:5], off
	v_lshl_add_u64 v[4:5], v[2:3], 0, s[8:9]
	v_readlane_b32 s8, v254, 41
	v_readlane_b32 s9, v254, 42
	global_load_dword v43, v[4:5], off
	v_readfirstlane_b32 s5, v1
	v_lshl_add_u64 v[4:5], v[2:3], 0, s[8:9]
	v_readlane_b32 s8, v254, 43
	v_readlane_b32 s9, v254, 44
	global_load_dword v45, v[4:5], off
	s_ashr_i32 s6, s5, 6
	v_lshl_add_u64 v[4:5], v[2:3], 0, s[8:9]
	v_readlane_b32 s8, v254, 45
	v_readlane_b32 s9, v254, 46
	global_load_dword v47, v[4:5], off
	v_mov_b32_e32 v10, s46
	v_lshl_add_u64 v[4:5], v[2:3], 0, s[8:9]
	v_readlane_b32 s8, v254, 47
	v_readlane_b32 s9, v254, 48
	global_load_dword v49, v[4:5], off
	v_mov_b32_e32 v11, s47
	v_lshl_add_u64 v[4:5], v[2:3], 0, s[8:9]
	v_readlane_b32 s8, v254, 49
	v_readlane_b32 s9, v254, 50
	global_load_dword v51, v[4:5], off
	s_mov_b32 s16, s67
	v_lshl_add_u64 v[4:5], v[2:3], 0, s[8:9]
	v_readlane_b32 s8, v254, 51
	v_readlane_b32 s9, v254, 52
	global_load_dword v53, v[4:5], off
	s_mov_b32 s14, s72
	v_lshl_add_u64 v[4:5], v[2:3], 0, s[8:9]
	v_readlane_b32 s8, v254, 53
	v_readlane_b32 s9, v254, 54
	global_load_dword v55, v[4:5], off
	v_readlane_b32 s64, v253, 34
	v_lshl_add_u64 v[4:5], v[2:3], 0, s[8:9]
	v_readlane_b32 s8, v254, 55
	v_readlane_b32 s9, v254, 56
	global_load_dword v57, v[4:5], off
	s_nop 0
	v_lshl_add_u64 v[4:5], v[2:3], 0, s[8:9]
	v_readlane_b32 s8, v254, 57
	v_readlane_b32 s9, v254, 58
	global_load_dword v59, v[4:5], off
	s_nop 0
	v_lshl_add_u64 v[4:5], v[2:3], 0, s[8:9]
	v_readlane_b32 s8, v254, 59
	v_readlane_b32 s9, v254, 60
	global_load_dword v61, v[4:5], off
	s_nop 0
	v_lshl_add_u64 v[4:5], v[2:3], 0, s[8:9]
	v_readlane_b32 s8, v254, 61
	v_readlane_b32 s9, v254, 62
	global_load_dword v63, v[4:5], off
	s_nop 0
	v_lshl_add_u64 v[4:5], v[2:3], 0, s[8:9]
	v_readlane_b32 s8, v254, 63
	v_readlane_b32 s9, v255, 0
	global_load_dword v65, v[4:5], off
	s_nop 0
	v_lshl_add_u64 v[4:5], v[2:3], 0, s[8:9]
	v_readlane_b32 s8, v255, 1
	v_readlane_b32 s9, v255, 2
	global_load_dword v67, v[4:5], off
	s_nop 0
	v_lshl_add_u64 v[4:5], v[2:3], 0, s[8:9]
	v_readlane_b32 s8, v255, 3
	v_readlane_b32 s9, v255, 4
	global_load_dword v69, v[4:5], off
	s_nop 0
	v_lshl_add_u64 v[4:5], v[2:3], 0, s[8:9]
	v_readlane_b32 s8, v255, 5
	v_readlane_b32 s9, v255, 6
	global_load_dword v71, v[4:5], off
	s_nop 0
	v_lshl_add_u64 v[4:5], v[2:3], 0, s[8:9]
	v_readlane_b32 s8, v255, 7
	v_readlane_b32 s9, v255, 8
	global_load_dword v73, v[4:5], off
	s_nop 0
	v_lshl_add_u64 v[4:5], v[2:3], 0, s[8:9]
	v_readlane_b32 s8, v255, 9
	v_readlane_b32 s9, v255, 10
	global_load_dword v75, v[4:5], off
	s_nop 0
	v_lshl_add_u64 v[4:5], v[2:3], 0, s[8:9]
	v_readlane_b32 s8, v255, 11
	v_readlane_b32 s9, v255, 12
	global_load_dword v77, v[4:5], off
	s_nop 0
	v_lshl_add_u64 v[4:5], v[2:3], 0, s[8:9]
	v_readlane_b32 s8, v255, 13
	v_readlane_b32 s9, v255, 14
	global_load_dword v79, v[4:5], off
	s_nop 0
	v_lshl_add_u64 v[4:5], v[2:3], 0, s[8:9]
	v_readlane_b32 s8, v255, 15
	v_readlane_b32 s9, v255, 16
	global_load_dword v81, v[4:5], off
	s_nop 0
	v_lshl_add_u64 v[4:5], v[2:3], 0, s[8:9]
	v_readlane_b32 s8, v255, 17
	v_readlane_b32 s9, v255, 18
	global_load_dword v83, v[4:5], off
	s_nop 0
	v_lshl_add_u64 v[4:5], v[2:3], 0, s[8:9]
	v_readlane_b32 s8, v255, 19
	v_readlane_b32 s9, v255, 20
	global_load_dword v85, v[4:5], off
	s_nop 0
	v_lshl_add_u64 v[4:5], v[2:3], 0, s[8:9]
	v_readlane_b32 s8, v255, 21
	v_readlane_b32 s9, v255, 22
	global_load_dword v87, v[4:5], off
	s_nop 0
	v_lshl_add_u64 v[4:5], v[2:3], 0, s[8:9]
	v_readlane_b32 s8, v254, 37
	v_readlane_b32 s9, v254, 38
	global_load_dword v89, v[4:5], off
	s_nop 0
	v_lshl_add_u64 v[4:5], v[2:3], 0, s[8:9]
	v_readlane_b32 s8, v254, 35
	v_readlane_b32 s9, v254, 36
	global_load_dword v91, v[4:5], off
	s_nop 0
	v_lshl_add_u64 v[4:5], v[2:3], 0, s[8:9]
	global_load_dword v93, v[4:5], off
	v_lshl_add_u64 v[4:5], v[2:3], 0, s[58:59]
	global_load_dword v95, v[4:5], off
	v_lshl_add_u64 v[4:5], v[2:3], 0, s[68:69]
	s_lshl_b64 s[8:9], s[84:85], 2
	global_load_dword v97, v[4:5], off
	v_lshl_add_u64 v[4:5], v[2:3], 0, s[94:95]
	v_lshl_add_u64 v[2:3], v[2:3], 0, s[88:89]
	s_add_u32 s10, s48, s8
	global_load_dword v99, v[4:5], off
	global_load_dword v101, v[2:3], off
	s_addc_u32 s11, s49, s9
	v_lshlrev_b32_e32 v2, 2, v1
	v_and_b32_e32 v12, 0xfc, v2
	s_add_u32 s8, s50, s8
	v_lshlrev_b32_e32 v6, 2, v12
	s_addc_u32 s9, s51, s9
	s_min_i32 s5, s6, 5
	global_load_dwordx4 v[2:5], v6, s[10:11]
	s_addk_i32 s5, 0x58
	v_readlane_b32 s10, v250, 32
	s_add_i32 s7, s5, s10
	v_lshlrev_b32_e32 v130, 1, v12
	s_max_i32 s7, s7, 0
	v_readlane_b32 s11, v250, 33
	s_min_i32 s28, s6, 13
	v_lshl_add_u64 v[102:103], s[80:81], 0, v[130:131]
	s_add_i32 s7, s7, s11
	s_addk_i32 s28, 0x50
	global_load_dwordx4 v[6:9], v6, s[8:9]
	v_mad_i64_i32 v[12:13], s[8:9], s7, v238, v[102:103]
	s_add_i32 s7, s28, s10
	s_max_i32 s7, s7, 0
	s_min_i32 s29, s6, 21
	s_add_i32 s7, s7, s11
	s_addk_i32 s29, 0x48
	global_load_dwordx2 v[108:109], v[12:13], off offset:1536
	global_load_dwordx2 v[106:107], v[12:13], off offset:1024
	v_mad_i64_i32 v[12:13], s[8:9], s7, v238, v[102:103]
	s_add_i32 s7, s29, s10
	s_max_i32 s7, s7, 0
	s_min_i32 s34, s6, 29
	s_add_i32 s7, s7, s11
	s_add_i32 s34, s34, 64
	global_load_dwordx2 v[112:113], v[12:13], off offset:1536
	global_load_dwordx2 v[110:111], v[12:13], off offset:1024
	v_mad_i64_i32 v[12:13], s[8:9], s7, v238, v[102:103]
	s_add_i32 s7, s34, s10
	s_max_i32 s7, s7, 0
	s_min_i32 s40, s6, 37
	s_add_i32 s7, s7, s11
	s_add_i32 s40, s40, 56
	global_load_dwordx2 v[116:117], v[12:13], off offset:1536
	global_load_dwordx2 v[114:115], v[12:13], off offset:1024
	v_mad_i64_i32 v[12:13], s[8:9], s7, v238, v[102:103]
	s_add_i32 s7, s40, s10
	s_max_i32 s7, s7, 0
	s_min_i32 s41, s6, 45
	s_add_i32 s7, s7, s11
	s_add_i32 s41, s41, 48
	global_load_dwordx2 v[120:121], v[12:13], off offset:1536
	global_load_dwordx2 v[118:119], v[12:13], off offset:1024
	v_mad_i64_i32 v[12:13], s[8:9], s7, v238, v[102:103]
	s_add_i32 s7, s41, s10
	s_max_i32 s7, s7, 0
	s_min_i32 s58, s6, 53
	s_add_i32 s7, s7, s11
	s_add_i32 s58, s58, 40
	global_load_dwordx2 v[124:125], v[12:13], off offset:1536
	global_load_dwordx2 v[122:123], v[12:13], off offset:1024
	v_mad_i64_i32 v[12:13], s[8:9], s7, v238, v[102:103]
	s_add_i32 s7, s58, s10
	s_max_i32 s7, s7, 0
	s_min_i32 s59, s6, 61
	s_add_i32 s7, s7, s11
	s_add_i32 s59, s59, 32
	global_load_dwordx2 v[128:129], v[12:13], off offset:1536
	global_load_dwordx2 v[126:127], v[12:13], off offset:1024
	v_mad_i64_i32 v[12:13], s[8:9], s7, v238, v[102:103]
	s_add_i32 s7, s59, s10
	s_max_i32 s7, s7, 0
	s_min_i32 s60, s6, 0x45
	s_add_i32 s7, s7, s11
	s_add_i32 s60, s60, 24
	global_load_dwordx2 v[134:135], v[12:13], off offset:1536
	global_load_dwordx2 v[132:133], v[12:13], off offset:1024
	v_mad_i64_i32 v[12:13], s[8:9], s7, v238, v[102:103]
	s_add_i32 s7, s60, s10
	s_max_i32 s7, s7, 0
	s_min_i32 s61, s6, 0x4d
	s_add_i32 s7, s7, s11
	s_add_i32 s61, s61, 16
	global_load_dwordx2 v[138:139], v[12:13], off offset:1536
	global_load_dwordx2 v[136:137], v[12:13], off offset:1024
	v_mad_i64_i32 v[12:13], s[8:9], s7, v238, v[102:103]
	s_add_i32 s7, s61, s10
	s_max_i32 s7, s7, 0
	s_min_i32 s62, s6, 0x55
	s_add_i32 s7, s7, s11
	s_add_i32 s62, s62, 8
	global_load_dwordx2 v[142:143], v[12:13], off offset:1536
	global_load_dwordx2 v[140:141], v[12:13], off offset:1024
	v_mad_i64_i32 v[12:13], s[8:9], s7, v238, v[102:103]
	s_add_i32 s7, s62, s10
	s_min_i32 s63, s6, 0x5d
	s_max_i32 s7, s7, 0
	s_add_i32 s6, s63, s10
	s_add_i32 s7, s7, s11
	s_max_i32 s6, s6, 0
	global_load_dwordx2 v[146:147], v[12:13], off offset:1536
	global_load_dwordx2 v[144:145], v[12:13], off offset:1024
	v_mad_i64_i32 v[12:13], s[8:9], s7, v238, v[102:103]
	s_add_i32 s6, s6, s11
	global_load_dwordx2 v[150:151], v[12:13], off offset:1536
	global_load_dwordx2 v[148:149], v[12:13], off offset:1024
	v_mad_i64_i32 v[12:13], s[6:7], s6, v238, v[102:103]
	global_load_dwordx2 v[154:155], v[12:13], off offset:1536
	global_load_dwordx2 v[152:153], v[12:13], off offset:1024
	v_or_b32_sdwa v12, v1, s84 dst_sel:DWORD dst_unused:UNUSED_PAD src0_sel:BYTE_0 src1_sel:DWORD
	v_ashrrev_i32_e32 v13, 31, v12
	v_lshl_add_u64 v[10:11], v[12:13], 2, v[10:11]
	global_load_dword v104, v[10:11], off
	s_waitcnt vmcnt(38)
	v_mov_b32_e32 v44, v43
	v_mov_b32_e32 v46, v45
	v_mov_b32_e32 v48, v47
	v_mov_b32_e32 v50, v49
	v_mov_b32_e32 v52, v51
	v_mov_b32_e32 v54, v53
	v_mov_b32_e32 v56, v55
	v_mov_b32_e32 v58, v57
	v_mov_b32_e32 v60, v59
	v_mov_b32_e32 v62, v61
	v_mov_b32_e32 v64, v63
	v_mov_b32_e32 v66, v65
	v_mov_b32_e32 v68, v67
	v_mov_b32_e32 v70, v69
	v_mov_b32_e32 v72, v71
	v_mov_b32_e32 v74, v73
	v_mov_b32_e32 v76, v75
	v_mov_b32_e32 v78, v77
	v_mov_b32_e32 v80, v79
	s_waitcnt vmcnt(37)
	v_mov_b32_e32 v82, v81
	s_waitcnt vmcnt(36)
	v_mov_b32_e32 v84, v83
	s_waitcnt vmcnt(35)
	v_mov_b32_e32 v86, v85
	s_waitcnt vmcnt(34)
	v_mov_b32_e32 v88, v87
	s_waitcnt vmcnt(33)
	v_mov_b32_e32 v90, v89
	s_waitcnt vmcnt(32)
	v_mov_b32_e32 v92, v91
	s_waitcnt vmcnt(31)
	v_mov_b32_e32 v94, v93
	s_waitcnt vmcnt(30)
	v_mov_b32_e32 v96, v95
	s_waitcnt vmcnt(29)
	v_mov_b32_e32 v98, v97
	s_waitcnt vmcnt(28)
	v_mov_b32_e32 v100, v99
	v_readlane_b32 s6, v253, 33
	s_branch .LBB0_320
